# pool units: GEMM weight fragments and scale loaded at unit start, all LDS fragment reads issued before the MFMAs
# speedup vs baseline: 1.0081x; 1.0081x over previous
; #define LAS __attribute__((address_space(3)))
; #define GAS __attribute__((address_space(1)))
; DI void pool_unit(const Ctx& C, const bf16_t* __restrict__ Z, bf16_t* __restrict__ Y, const bf16_t* cwT  , const float* cscale, int tile, int g) {
;     ...
;     const int R0 = tile * 64;
;     int S0, S1; if (R0 < NLAT) { S0 = R0 & ~(SEQ - 1); S1 = S0 + SEQ; } else { S0 = NLAT + ((R0 - NLAT) & ~(CTXL - 1)); S1 = S0 + CTXL; }
;     LAS float* U = (LAS float*)C.lds;
;     LAS bf16_t* P = (LAS bf16_t*)(C.lds + 80 * 132 * 4);
;     __syncthreads();
;     { u32x4 vv[3];
; #pragma unroll
;       for (int k = 0; k < 3; ++k) { const int i = tid + k * NTHREADS, rr = i >> 4, ch = i & 15, grow = R0 - 8 + rr;
;           vv[k] = (u32x4){0u, 0u, 0u, 0u};
;           if (i < 80 * 16 && grow >= S0 && grow < S1) vv[k] = *(const GAS u32x4*)(Z + (size_t)grow * ZW + Z_CU + 128 * g + 8 * ch); }
;     ...
;     const bf16_t* wp = cwT + ((size_t)g * 128 + 16 * w + l15) * 128 + 8 * quad;
; #pragma unroll
;     for (int kc = 0; kc < 4; ++kc) { const bf16x8 a = *(const GAS bf16x8*)(wp + 32 * kc);
; #pragma unroll
;         for (int tb = 0; tb < 4; ++tb) { const bf16x8 bb = *(const LAS bf16x8*)(P + (16 * tb + l15) * 136 + 32 * kc + 8 * quad);
;             acc[tb] = __builtin_amdgcn_mfma_f32_16x16x32_bf16(a, bb, acc[tb], 0, 0, 0); } }
;     const int e0 = 128 * g + 16 * w + 4 * quad; const f32x4 sc = *(const GAS f32x4*)(cscale + e0);
.LBB0_509:
	s_ashr_i32 s16, s19, 2
	s_lshl_b32 s20, s16, 6
	s_and_b32 s17, s20, 0xfffff800
	s_and_b32 s24, s20, 0x7fffff00
	s_and_b32 s23, s19, 3
	s_add_i32 s21, s17, 0x800
	s_add_i32 s22, s24, 0x100
	s_cmpk_lt_i32 s16, 0x80
	s_cselect_b32 s22, s21, s22
	s_cselect_b32 s21, s17, s24
	s_add_i32 s24, s20, -8
	v_add_u32_e32 v29, s24, v44
	v_cmp_le_i32_e32 vcc, s21, v29
	s_and_b64 s[16:17], s[0:1], vcc
	v_cmp_gt_i32_e32 vcc, s22, v29
	s_lshl_b32 s36, s23, 7
	s_and_b64 s[26:27], s[16:17], vcc
	v_lshl_add_u64 v[146:147], v[40:41], 0, s[36:37]
	v_lshlrev_b64 v[146:147], 8, v[146:147]
	v_lshl_add_u64 v[146:147], v[42:43], 0, v[146:147]
	global_load_dwordx4 v[72:75], v[146:147], off
	global_load_dwordx4 v[76:79], v[146:147], off offset:64
	global_load_dwordx4 v[80:83], v[146:147], off offset:128
	global_load_dwordx4 v[138:141], v[146:147], off offset:192
	v_add_u32_e32 v148, s36, v49
	v_ashrrev_i32_e32 v149, 31, v148
	v_lshl_add_u64 v[148:149], v[148:149], 2, s[14:15]
	global_load_dwordx4 v[142:145], v[148:149], off
	v_mov_b32_e32 v28, 0
	v_lshlrev_b32_e32 v0, 1, v2
	v_mov_b32_e32 v32, 0
	v_mov_b32_e32 v33, 0
	v_mov_b32_e32 v34, 0
	v_mov_b32_e32 v35, 0
	s_barrier
	s_and_saveexec_b64 s[16:17], s[26:27]
	s_cbranch_execz .LBB0_511
	v_mov_b64_e32 v[30:31], s[8:9]
	v_mad_i64_i32 v[30:31], s[26:27], v29, s53, v[30:31]
	s_lshl_b32 s26, s36, 1
	s_mov_b32 s27, s37
	v_lshl_add_u64 v[30:31], v[30:31], 0, s[26:27]
	v_lshl_add_u64 v[30:31], v[30:31], 0, v[0:1]
	v_add_co_u32_e32 v30, vcc, 0x1000, v30
	s_nop 1
	v_addc_co_u32_e32 v31, vcc, 0, v31, vcc
	global_load_dwordx4 v[32:35], v[30:31], off offset:512

; #define LAS __attribute__((address_space(3)))
; #define GAS __attribute__((address_space(1)))
; DI unsigned pk2(float lo, float hi) { f32x2 v = {lo, hi}; bf16x2_t b = __builtin_convertvector(v, bf16x2_t); return __builtin_bit_cast(unsigned, b); }
; DI void pool_unit(const Ctx& C, const bf16_t* __restrict__ Z, bf16_t* __restrict__ Y, const bf16_t* cwT  , const float* cscale, int tile, int g) {
;     ...
;     { const int wsz = 2 << g, hw = wsz >> 1, ch = tid & 127, tg = tid >> 7;
;       const LAS float* up = U + ch; const int t0 = tg * 16;
;       float s = 0.f; for (int rr = t0 + 8 - hw; rr < t0 + 8 - hw + wsz; ++rr) s += up[rr * 132];
;       for (int tt = 0; tt < 16; ++tt) { const int t = t0 + tt, grow = R0 + t; const int lo = max(grow - hw, S0), hi = min(grow + wsz - 1 - hw, S1 - 1);
;           const float pooled = s / (float)(hi - lo + 1) - up[(t + 8) * 132];
;           P[t * 136 + ch] = (bf16_t)(pk2(pooled, 0.f) & 0xffffu);
;           s += up[(t + 8 - hw + wsz) * 132] - up[(t + 8 - hw) * 132]; } }
;     __syncthreads();
;     f32x4 acc[4];
; #pragma unroll
;     for (int tb = 0; tb < 4; ++tb) acc[tb] = (f32x4){0.f, 0.f, 0.f, 0.f};
;     const bf16_t* wp = cwT + ((size_t)g * 128 + 16 * w + l15) * 128 + 8 * quad;
; #pragma unroll
;     for (int kc = 0; kc < 4; ++kc) { const bf16x8 a = *(const GAS bf16x8*)(wp + 32 * kc);
; #pragma unroll
;         for (int tb = 0; tb < 4; ++tb) { const bf16x8 bb = *(const LAS bf16x8*)(P + (16 * tb + l15) * 136 + 32 * kc + 8 * quad);
;             acc[tb] = __builtin_amdgcn_mfma_f32_16x16x32_bf16(a, bb, acc[tb], 0, 0, 0); } }
;     const int e0 = 128 * g + 16 * w + 4 * quad; const f32x4 sc = *(const GAS f32x4*)(cscale + e0);
; #pragma unroll
;     for (int tb = 0; tb < 4; ++tb) { const f32x4 v = acc[tb] * sc; u32x2 wv; wv.x = pk2(v[0], v[1]); wv.y = pk2(v[2], v[3]);
;         *(GAS u32x2*)(Y + (size_t)(R0 + 16 * tb + l15) * DM + 1024 + e0) = wv; }
.LBB0_524:
	v_add_u32_e32 v58, s17, v28
	v_add_u32_e32 v57, s17, v29
	v_add_u32_e32 v35, -1, v58
	v_max_i32_e32 v34, s21, v57
	v_min_i32_e32 v35, s16, v35
	v_sub_u32_e32 v34, v35, v34
	v_add_u32_e32 v34, 1, v34
	v_cvt_f32_i32_e32 v34, v34
	v_add_u32_e32 v59, 0, v33
	s_add_i32 s17, s17, 2
	v_add_u32_e32 v33, 0x220, v33
	v_div_scale_f32 v35, s[22:23], v34, v34, v0
	v_rcp_f32_e32 v36, v35
	s_cmp_lg_u32 s17, 16
	v_fma_f32 v37, -v35, v36, 1.0
	v_fmac_f32_e32 v36, v37, v36
	v_div_scale_f32 v37, vcc, v0, v34, v0
	v_mul_f32_e32 v38, v37, v36
	v_fma_f32 v39, -v35, v38, v37
	v_fmac_f32_e32 v38, v39, v36
	v_fma_f32 v35, -v35, v38, v37
	v_div_fmas_f32 v35, v35, v36, v38
	v_div_fixup_f32 v36, v35, v34, v0
	v_add_u32_e32 v34, 0, v32
	ds_read2_b32 v[34:35], v34 offset1:132
	v_add_u32_e32 v32, 0x420, v32
	s_waitcnt lgkmcnt(0)
	v_sub_f32_e32 v34, v36, v34
	v_cvt_pk_bf16_f32 v34, v34, s0
	ds_write_b16 v59, v34
	v_add_u32_e32 v34, 0, v31
	ds_read2_b32 v[36:37], v34 offset1:132
	v_add_u32_e32 v34, 0, v30
	ds_read2_b32 v[38:39], v34 offset1:132
	v_add_u32_e32 v30, 0x420, v30
	v_add_u32_e32 v31, 0x420, v31
	s_waitcnt lgkmcnt(0)
	v_sub_f32_e32 v34, v36, v38
	v_add_f32_e32 v0, v0, v34
	v_add_u32_e32 v34, 1, v57
	v_max_i32_e32 v34, s21, v34
	v_min_i32_e32 v36, s16, v58
	v_sub_u32_e32 v34, v36, v34
	v_add_u32_e32 v34, 1, v34
	v_cvt_f32_i32_e32 v34, v34
	v_div_scale_f32 v36, s[22:23], v34, v34, v0
	v_rcp_f32_e32 v38, v36
	s_nop 0
	v_fma_f32 v57, -v36, v38, 1.0
	v_fmac_f32_e32 v38, v57, v38
	v_div_scale_f32 v57, vcc, v0, v34, v0
	v_mul_f32_e32 v58, v57, v38
	v_fma_f32 v60, -v36, v58, v57
	v_fmac_f32_e32 v58, v60, v38
	v_fma_f32 v36, -v36, v58, v57
	v_div_fmas_f32 v36, v36, v38, v58
	v_div_fixup_f32 v34, v36, v34, v0
	v_sub_f32_e32 v34, v34, v35
	v_cvt_pk_bf16_f32 v34, v34, s0
	ds_write_b16 v59, v34 offset:272
	v_sub_f32_e32 v34, v37, v39
	v_add_f32_e32 v0, v0, v34
	s_cbranch_scc1 .LBB0_524
	s_waitcnt lgkmcnt(0)
	s_barrier
	ds_read_b128 v[32:35], v56 offset:42240
	ds_read_b128 v[36:39], v56 offset:46592
	ds_read_b128 v[58:61], v56 offset:50944
	ds_read_b128 v[62:65], v56 offset:55296
	ds_read_b128 v[66:69], v56 offset:42304
	ds_read_b128 v[210:213], v56 offset:46656
	ds_read_b128 v[214:217], v56 offset:51008
	ds_read_b128 v[218:221], v56 offset:55360
	ds_read_b128 v[222:225], v56 offset:42368
	ds_read_b128 v[240:243], v56 offset:46720
	ds_read_b128 v[244:247], v56 offset:51072
	ds_read_b128 v[182:185], v56 offset:55424
	ds_read_b128 v[186:189], v56 offset:42432
	ds_read_b128 v[190:193], v56 offset:46784
	ds_read_b128 v[150:153], v56 offset:51136
	ds_read_b128 v[158:161], v56 offset:55488
	s_add_i32 s19, s19, s48
	s_cmp_ge_i32 s19, s18
	s_waitcnt vmcnt(0) lgkmcnt(15)
	v_mfma_f32_16x16x32_bf16 v[32:35], v[72:75], v[32:35], 0
	s_waitcnt lgkmcnt(14)
	v_mfma_f32_16x16x32_bf16 v[36:39], v[72:75], v[36:39], 0
	s_waitcnt lgkmcnt(13)
	v_mfma_f32_16x16x32_bf16 v[58:61], v[72:75], v[58:61], 0
	s_waitcnt lgkmcnt(12)
	v_mfma_f32_16x16x32_bf16 v[28:31], v[72:75], v[62:65], 0
	s_waitcnt lgkmcnt(11)
	v_mfma_f32_16x16x32_bf16 v[32:35], v[76:79], v[66:69], v[32:35]
	s_waitcnt lgkmcnt(10)
	v_mfma_f32_16x16x32_bf16 v[36:39], v[76:79], v[210:213], v[36:39]
	s_waitcnt lgkmcnt(9)
	v_mfma_f32_16x16x32_bf16 v[58:61], v[76:79], v[214:217], v[58:61]
	s_waitcnt lgkmcnt(8)
	v_mfma_f32_16x16x32_bf16 v[28:31], v[76:79], v[218:221], v[28:31]
	s_waitcnt lgkmcnt(7)
	v_mfma_f32_16x16x32_bf16 v[32:35], v[80:83], v[222:225], v[32:35]
	s_waitcnt lgkmcnt(6)
	v_mfma_f32_16x16x32_bf16 v[36:39], v[80:83], v[240:243], v[36:39]
	s_waitcnt lgkmcnt(5)
	v_mfma_f32_16x16x32_bf16 v[58:61], v[80:83], v[244:247], v[58:61]
	s_waitcnt lgkmcnt(4)
	v_mfma_f32_16x16x32_bf16 v[28:31], v[80:83], v[182:185], v[28:31]
	s_waitcnt lgkmcnt(3)
	v_mfma_f32_16x16x32_bf16 v[32:35], v[138:141], v[186:189], v[32:35]
	s_waitcnt lgkmcnt(2)
	v_mfma_f32_16x16x32_bf16 v[36:39], v[138:141], v[190:193], v[36:39]
	s_waitcnt lgkmcnt(1)
	v_mfma_f32_16x16x32_bf16 v[58:61], v[138:141], v[150:153], v[58:61]
	s_waitcnt lgkmcnt(0)
	v_mfma_f32_16x16x32_bf16 v[28:31], v[138:141], v[158:161], v[28:31]
	s_nop 1
	v_add_u32_e32 v66, s36, v49
	v_ashrrev_i32_e32 v67, 31, v66
	v_or_b32_e32 v68, s20, v3
	v_ashrrev_i32_e32 v69, 31, v68
	v_lshlrev_b64 v[66:67], 1, v[66:67]
	v_pk_mul_f32 v[34:35], v[34:35], v[144:145]
	v_pk_mul_f32 v[32:33], v[32:33], v[142:143]
	v_pk_mul_f32 v[30:31], v[30:31], v[144:145]
	v_cvt_pk_bf16_f32 v32, v32, v33
	v_cvt_pk_bf16_f32 v33, v34, v35
	v_lshlrev_b64 v[34:35], 12, v[68:69]
	v_lshl_add_u64 v[34:35], s[10:11], 0, v[34:35]
	v_lshl_add_u64 v[34:35], v[34:35], 0, v[66:67]
	global_store_dwordx2 v[34:35], v[32:33], off offset:2048
	v_pk_mul_f32 v[32:33], v[38:39], v[144:145]
	v_pk_mul_f32 v[34:35], v[36:37], v[142:143]
	v_pk_mul_f32 v[28:29], v[28:29], v[142:143]
	v_cvt_pk_bf16_f32 v34, v34, v35
	v_cvt_pk_bf16_f32 v35, v32, v33
	v_or_b32_e32 v32, 16, v68
	v_ashrrev_i32_e32 v33, 31, v32
	v_lshlrev_b64 v[32:33], 12, v[32:33]
	v_lshl_add_u64 v[32:33], s[10:11], 0, v[32:33]
	v_lshl_add_u64 v[32:33], v[32:33], 0, v[66:67]
	global_store_dwordx2 v[32:33], v[34:35], off offset:2048
	v_pk_mul_f32 v[32:33], v[60:61], v[144:145]
	v_pk_mul_f32 v[34:35], v[58:59], v[142:143]
	v_cvt_pk_bf16_f32 v28, v28, v29
	v_cvt_pk_bf16_f32 v34, v34, v35
	v_cvt_pk_bf16_f32 v35, v32, v33
	v_or_b32_e32 v32, 32, v68
	v_cvt_pk_bf16_f32 v29, v30, v31
	v_or_b32_e32 v30, 48, v68
	v_ashrrev_i32_e32 v33, 31, v32
	v_ashrrev_i32_e32 v31, 31, v30
	v_lshlrev_b64 v[32:33], 12, v[32:33]
	v_lshlrev_b64 v[30:31], 12, v[30:31]
	v_lshl_add_u64 v[32:33], s[10:11], 0, v[32:33]
	v_lshl_add_u64 v[30:31], s[10:11], 0, v[30:31]
	v_lshl_add_u64 v[32:33], v[32:33], 0, v[66:67]
	v_lshl_add_u64 v[30:31], v[30:31], 0, v[66:67]
	global_store_dwordx2 v[32:33], v[34:35], off offset:2048
	global_store_dwordx2 v[30:31], v[28:29], off offset:2048
	s_cbranch_scc0 .LBB0_509
